# FFN2-up weight conversion split: 768 items into the P1 idle-workgroup conversion loop (4 items per wave), 2048 stay in P8 (one item per wave); copy lives in d_out until P9
# baseline (speedup 1.0000x reference)
; __device__ __forceinline__ void convert_mid(const Ctx& C, int vbid, int vG) {
;     ...
;     constexpr int I1 = 16 * 88, I2 = 44 * 32, IO = 16 * 32, NIT = I1 + I2 + IO;
;     for (int it = gw; it < NIT; it += NGW) {
;         int r = it;
;         if (r < I2) { transpose_item(C.in[5], FF_, D_, nullptr, W2, 0, scr, r, lane); continue; } r -= I2;
;         if (r < I1) { transpose_item(C.in[7], D_, FF_, C.in[6], Win, 0, scr, r, lane); continue; } r -= I1;
;         transpose_item(C.in[23], D_, D_, nullptr, Wout, 0, scr, r, lane);
;     }
.Lmy_c1_loop:
	s_cmp_ge_i32 s2, 0x1000
	s_cbranch_scc1 .Lmy_c1_exit
	s_cmp_ge_i32 s2, 0x580
	s_cbranch_scc1 .Lmy_c1_seg1
	s_mov_b32 s15, s2
	s_mov_b32 s16, 0x8000001
	s_mul_hi_u32 s14, s15, s16
	s_mul_i32 s16, s14, 32
	s_sub_i32 s15, s15, s16
	s_load_dwordx2 s[4:5], s[100:101], 0x28
	s_mov_b64 s[18:19], 0
	s_add_u32 s52, s26, 0xa300000
	s_addc_u32 s53, s27, 0
	s_mov_b32 s6, 0x1000
	s_mov_b32 s54, 0x1600
	s_mov_b32 s56, 0
	s_waitcnt lgkmcnt(0)
	s_branch .Lmy_c1_item

; __device__ __forceinline__ void convert_mid(const Ctx& C, int vbid, int vG) {
;     ...
;     for (int it = gw; it < NIT; it += NGW) {
;         int r = it;
;         if (r < I2) { transpose_item(C.in[5], FF_, D_, nullptr, W2, 0, scr, r, lane); continue; } r -= I2;
;         if (r < I1) { transpose_item(C.in[7], D_, FF_, C.in[6], Win, 0, scr, r, lane); continue; } r -= I1;
;         transpose_item(C.in[23], D_, D_, nullptr, Wout, 0, scr, r, lane);
;     }
; __device__ __forceinline__ void convert_w13b(const Ctx& C) {
;     ...
;     constexpr int I1 = 16 * 88;
;     for (int it = gw; it < 2 * I1; it += NGW) {
;         if (it < I1) transpose_item(C.in[25], D_, FF_, C.in[24], W13, 1, scr, it, lane);
;         else transpose_item(C.in[26], D_, FF_, C.in[24], W13, 2, scr, it - I1, lane);
.Lmy_c1_seg2:
	s_cmp_ge_i32 s2, 0xd00
	s_cbranch_scc1 .Lmy_c1_seg3
	s_sub_i32 s15, s2, 0xb00
	s_mov_b32 s16, 0x8000001
	s_mul_hi_u32 s14, s15, s16
	s_mul_i32 s16, s14, 32
	s_sub_i32 s15, s15, s16
	s_load_dwordx2 s[4:5], s[100:101], 0xb8
	s_mov_b64 s[18:19], 0
	s_add_u32 s52, s26, 0xfc00000
	s_addc_u32 s53, s27, 0
	s_mov_b32 s6, 0x1000
	s_mov_b32 s54, 0x800
	s_mov_b32 s56, 0
	s_waitcnt lgkmcnt(0)
	s_branch .Lmy_c1_item
.Lmy_c1_seg3:
	s_sub_i32 s15, s2, 0xd00
	s_mov_b32 s16, 0x2e8ba2f
	s_mul_hi_u32 s14, s15, s16
	s_mul_i32 s16, s14, 88
	s_sub_i32 s15, s15, s16
	s_load_dwordx2 s[4:5], s[100:101], 0xc8
	s_load_dwordx2 s[18:19], s[100:101], 0xc0
	s_add_u32 s52, s24, 0x0
	s_addc_u32 s53, s25, 0
	s_mov_b32 s6, 0x2c00
	s_mov_b32 s54, 0x800
	s_mov_b32 s56, 1
	s_waitcnt lgkmcnt(0)

; #define LAS __attribute__((address_space(3)))
; __device__ __forceinline__ void convert_w13b(const Ctx& C) {
;     LAS float* scr = (LAS float*)(C.lds + C.wave * 8448);
;     const int gw = C.bid * 8 + C.wave, NGW = C.G * 8, lane = C.lane;
;     bf16_t* W13 = (bf16_t*)(C.ws + WS_W13B);
;     constexpr int I1 = 16 * 88;
;     for (int it = gw; it < 2 * I1; it += NGW) {
;         if (it < I1) transpose_item(C.in[25], D_, FF_, C.in[24], W13, 1, scr, it, lane);
;         else transpose_item(C.in[26], D_, FF_, C.in[24], W13, 2, scr, it - I1, lane);
;     }
; }
.LBB0_1122:
	v_readlane_b32 s0, v254, 1
	v_readlane_b32 s1, v254, 2
	s_load_dwordx16 s[8:23], s[0:1], 0xc0
	s_cmp_lt_i32 s76, 9
	s_cselect_b64 s[0:1], -1, 0
	s_and_b64 s[44:45], s[0:1], s[6:7]
	s_andn2_b64 vcc, exec, s[44:45]
	s_cbranch_vccnz .LBB0_1298
	s_waitcnt lgkmcnt(0)
	s_lshl_b32 s2, s94, 3
	s_add_i32 s2, s80, s2
	s_addk_i32 s2, 0x300
	s_lshl_b32 s3, s88, 3
	v_readlane_b32 s100, v254, 1
	v_readlane_b32 s101, v254, 2
	v_and_b32_e32 v1, 31, v193
	v_lshrrev_b32_e32 v2, 5, v193
	v_and_b32_e32 v3, 7, v193
	v_lshrrev_b32_e32 v4, 3, v193
	s_mul_i32 s30, s80, 0x2100
	v_mad_u32_u24 v5, v2, 33, v1
	v_lshl_add_u32 v5, v5, 2, s30
	v_mul_u32_u24_e32 v6, 0x108, v3
	v_add_u32_e32 v6, v6, v4
	v_lshl_add_u32 v6, v6, 2, s30
.Lmy_c8_loop:
	s_cmp_ge_i32 s2, 0xb00
	s_cbranch_scc1 .Lmy_c8_exit
	s_cmp_ge_i32 s2, 0x580
	s_cbranch_scc1 .Lmy_c8_seg1
	s_mov_b32 s29, s2
	s_mov_b32 s30, 0x2e8ba2f
	s_mul_hi_u32 s28, s29, s30
	s_mul_i32 s30, s28, 88
	s_sub_i32 s29, s29, s30
	s_load_dwordx2 s[4:5], s[100:101], 0xc8
	s_load_dwordx2 s[34:35], s[100:101], 0xc0
	s_add_u32 s10, s24, 0x0
	s_addc_u32 s11, s25, 0
	s_mov_b32 s6, 0x2c00
	s_mov_b32 s12, 0x800
	s_mov_b32 s13, 1
	s_waitcnt lgkmcnt(0)
	s_branch .Lmy_c8_item
.Lmy_c8_seg1:
	s_sub_i32 s29, s2, 0x580
	s_mov_b32 s30, 0x2e8ba2f
	s_mul_hi_u32 s28, s29, s30
	s_mul_i32 s30, s28, 88
	s_sub_i32 s29, s29, s30
	s_load_dwordx2 s[4:5], s[100:101], 0xd0
	s_load_dwordx2 s[34:35], s[100:101], 0xc0
	s_add_u32 s10, s24, 0x0
	s_addc_u32 s11, s25, 0
	s_mov_b32 s6, 0x2c00
	s_mov_b32 s12, 0x800
	s_mov_b32 s13, 2
	s_waitcnt lgkmcnt(0)

;     __host__ __device__ bool next(int i, Unit& u) const {
;         const long L = (long)i * G + c; if (L >= nwg) return false;
;         int wgid = (int)L; { const int q = nwg / NXCD, r = nwg % NXCD, xcd = wgid % NXCD, off = wgid / NXCD; wgid = (xcd < r ? xcd * (q + 1) : r * (q + 1) + (xcd - r) * q) + off; }
;         const int nig = WGM * nN, gid = wgid / nig, fm = gid * WGM, gsz = (nM - fm) < WGM ? (nM - fm) : WGM;
;         u.pm = fm + ((wgid % nig) % gsz); u.pn = (wgid % nig) / gsz; return true;
;     }
; __device__ __forceinline__ unsigned cvt_pk_bf16(float lo, float hi) { unsigned r; asm volatile("v_cvt_pk_bf16_f32 %0, %1, %2" : "=v"(r) : "v"(lo), "v"(hi)); return r; }
; template <class Epi, class Sched, bool ALIGN_EPI = false, bool SP2 = false>
; __device__ __forceinline__ void gemm_phase(PG8_LAS unsigned char* lds, const Gemm g, const Sched& S, const Epi& E) {
;     const int tid = threadIdx.x, wid = __builtin_amdgcn_readfirstlane(tid >> 6), lane = tid & 63, wr = wid >> 2, wc = wid & 3, fr = lane & 15, fq = lane >> 4;
;     const int K = g.K, nt = K / BK;
;     unsigned voffA[2], voffB[2];
; #pragma unroll
;     for (int i = 0; i < 2; ++i) { int R, C; stage_rc(tid * 16 + i * 8192, R, C); const int Rb = Epi::PERM ? ((R & ~31) + perm32(R & 31)) : R;
;         voffA[i] = (unsigned)(R * K + C) * 2u; voffB[i] = (unsigned)(Rb * K + C) * 2u; }
;     const size_t kstep = (size_t)(BK * 2);
;     const size_t hstep = (size_t)HALF * K * 2;
;     const size_t tstep = 2 * hstep;
;     const unsigned ldsw = (unsigned)wid * 1024u;
;     const int aoff = lds_byte(wr * 64 + fr, fq * 8), boff = lds_byte(wc * 32 + fr, fq * 8);
;     ...
;     Unit cur, nxt; int ui = 0;
;     if (!S.next(0, cur)) return;
;     f32x4 acc[2][2][4][2];
; #pragma unroll
;     for (int a = 0; a < 2; ++a)
; #pragma unroll
;         for (int b = 0; b < 2; ++b)
; #pragma unroll
;             for (int m = 0; m < 4; ++m)
; #pragma unroll
;                 for (int n = 0; n < 2; ++n) acc[a][b][m][n] = (f32x4){0.f, 0.f, 0.f, 0.f};
;     bf16x8 At[4][2], B0[2][2], B1[2][2];
; __global__ void __launch_bounds__(NTHR, 2) fwd_kernel(Args args) {
;     ...
;     if (IN(9)) {
;         pg8::Gemm g{actB, (const bf16_t*)(ws + WS_W13B), T_, 2 * FF_, D_}; pg8::StaticOrder S; S.init(T_, 2 * FF_, C.G, C.bid);
;         EpiSwiGLU E{hid, ssqA};
;         pg8::gemm_phase<EpiSwiGLU, pg8::StaticOrder, true, true>(C.lds, g, S, E);
.LBB0_1352:
	s_mov_b32 s100, -1
	s_cmp_lt_i32 s76, 10
	s_cselect_b64 s[2:3], -1, 0
	s_waitcnt lgkmcnt(0)
	s_and_b64 s[8:9], s[2:3], s[0:1]
	s_andn2_b64 vcc, exec, s[8:9]
	s_cbranch_vccnz .LBB0_1533
	s_cmpk_gt_i32 s94, 0x57f
	v_readfirstlane_b32 s1, v0
	s_cbranch_scc1 .LBB0_1369
	v_lshrrev_b32_e32 v1, 5, v0
	v_lshrrev_b32_e32 v3, 1, v0
	v_and_b32_e32 v1, 4, v1
	v_bfe_u32 v2, v0, 2, 2
	v_and_b32_e32 v3, 24, v3
	v_or3_b32 v1, v1, v2, v3
	v_lshlrev_b32_e32 v2, 4, v0
	v_or_b32_e32 v10, 0x2000, v2
	s_add_u32 s2, s24, 0
	v_lshrrev_b32_e32 v3, 7, v10
	s_movk_i32 s0, 0x60
	s_addc_u32 s3, s25, 0
	v_and_or_b32 v4, v3, s0, v1
	v_bfe_u32 v13, v0, 2, 4
	s_movk_i32 s0, 0x70
	s_ashr_i32 s5, s94, 31
	v_and_or_b32 v3, v3, s0, v13
	s_lshr_b32 s0, s5, 29
	s_add_i32 s0, s94, s0
	s_lshr_b32 s12, s1, 6
	s_ashr_i32 s6, s0, 3
	s_and_b32 s0, s0, -8
	s_lshr_b32 s37, s1, 8
	s_lshl_b32 s4, s12, 10
	s_sub_i32 s0, s94, s0
	s_cmp_lt_i32 s0, 0
	s_movk_i32 s28, 0xb1
	s_cselect_b32 s7, s28, 0xb0
	s_mul_i32 s0, s0, s7
	s_add_i32 s0, s0, s6
	s_mul_hi_i32 s6, s0, 0x2e8ba2e9
	s_lshr_b32 s7, s6, 31
	s_ashr_i32 s6, s6, 5
	s_add_i32 s6, s6, s7
	s_lshl_b32 s7, s6, 3
	s_mulk_i32 s6, 0xb0
	s_sub_i32 s6, s0, s6
	s_sext_i32_i16 s0, s6
	s_bfe_u32 s0, s0, 0x3001c
	s_add_i32 s10, s6, s0
	s_sext_i32_i16 s0, s10
	s_and_b32 s10, s10, 0xfff8
	s_sub_i32 s6, s6, s10
	s_sext_i32_i16 s6, s6
	v_and_b32_e32 v5, 32, v0
	s_lshr_b32 s0, s0, 3
	s_add_i32 s6, s7, s6
	v_bitop3_b32 v11, v2, v5, 48 bitop3:0x6c
	v_and_b32_e32 v12, 64, v0
	s_ashr_i32 s7, s6, 31
	s_bfe_i64 s[30:31], s[0:1], 0x100000
	v_or_b32_e32 v2, v11, v12
	s_lshl_b64 s[10:11], s[6:7], 19
	s_lshl_b64 s[30:31], s[30:31], 19
	s_waitcnt vmcnt(0)
	v_lshl_or_b32 v132, v3, 11, v2
	v_lshrrev_b32_e32 v3, 3, v0
	s_add_u32 s54, s2, s30
	v_and_or_b32 v1, v3, 32, v1
	s_addc_u32 s55, s3, s31
	s_add_i32 s29, s4, 0
	v_lshl_or_b32 v134, v1, 11, v2
	s_add_i32 m0, s29, 0x10000
	v_lshl_or_b32 v130, v4, 11, v2
	global_load_lds_dwordx4 v134, s[54:55]
	s_add_i32 m0, s29, 0x12000
	s_add_u32 s30, s54, 0x40000
	global_load_lds_dwordx4 v130, s[54:55]
	s_addc_u32 s31, s55, 0
	s_add_i32 m0, s29, 0x14000
	v_and_or_b32 v1, v3, 48, v13
	global_load_lds_dwordx4 v134, s[30:31]
	s_add_i32 m0, s29, 0x16000
	s_add_u32 s52, s84, s10
	global_load_lds_dwordx4 v130, s[30:31]
	s_addc_u32 s53, s85, s11
	s_add_i32 s30, s29, 0x2000
	v_lshl_or_b32 v136, v1, 11, v2
	s_mov_b32 m0, s29
	s_add_u32 s10, s52, 0x40000
	global_load_lds_dwordx4 v136, s[52:53]
	s_mov_b32 m0, s30
	s_addc_u32 s11, s53, 0
	s_add_i32 s31, s29, 0x4000
	global_load_lds_dwordx4 v132, s[52:53]
	s_mov_b32 m0, s31
	s_add_i32 s33, s29, 0x6000
	global_load_lds_dwordx4 v136, s[10:11]
	s_mov_b32 m0, s33
	v_mov_b32_e32 v135, 0
	global_load_lds_dwordx4 v132, s[10:11]
	v_mov_b32_e32 v131, v135
	v_mov_b32_e32 v137, v135
	v_mov_b32_e32 v133, v135
	s_cmp_eq_u32 s37, 1
	s_mov_b32 s34, 0
	v_lshl_add_u64 v[8:9], s[54:55], 0, v[134:135]
	v_lshl_add_u64 v[6:7], s[54:55], 0, v[130:131]
	v_lshl_add_u64 v[2:3], s[52:53], 0, v[136:137]
	s_cselect_b64 s[10:11], -1, 0
	s_cmp_lg_u32 s37, 1
	v_lshl_add_u64 v[4:5], s[52:53], 0, v[132:133]
	s_cbranch_scc1 .LBB0_1356
	s_barrier
